# P0 prologue: parameter pack copies with 16 quads per thread in flight; adaLN conditioning loads requested together
# speedup vs baseline: 1.6036x; 1.0053x over previous
.LBB0_58:
	v_mov_b64_e32 v[56:57], v[20:21]
	global_load_dword v46, v[56:57], off
	v_lshl_add_u64 v[56:57], v[56:57], 0, s[54:55]
	global_load_dword v47, v[56:57], off
	v_lshl_add_u64 v[56:57], v[56:57], 0, s[54:55]
	global_load_dword v48, v[56:57], off
	v_lshl_add_u64 v[56:57], v[56:57], 0, s[54:55]
	global_load_dword v49, v[56:57], off
	v_lshl_add_u64 v[56:57], v[56:57], 0, s[54:55]
	global_load_dword v50, v[56:57], off
	v_lshl_add_u64 v[56:57], v[56:57], 0, s[54:55]
	global_load_dword v51, v[56:57], off
	v_lshl_add_u64 v[56:57], v[56:57], 0, s[54:55]
	global_load_dword v52, v[56:57], off
	v_lshl_add_u64 v[56:57], v[56:57], 0, s[54:55]
	global_load_dword v53, v[56:57], off
	v_lshl_add_u64 v[56:57], v[56:57], 0, s[54:55]
	v_and_b32_e32 v4, 0x3ff, v19
	v_lshlrev_b32_e32 v4, 2, v4
	v_lshl_add_u64 v[56:57], s[66:67], 0, v[4:5]
	global_load_dword v54, v[56:57], off
	global_load_dword v55, v[56:57], off offset:2048
	s_waitcnt vmcnt(9)
	v_mul_f32_e32 v22, 0xbfb8aa3b, v46
	v_exp_f32_e32 v22, v22
	s_nop 0
	v_add_f32_e32 v22, 1.0, v22
	v_div_scale_f32 v23, s[56:57], v22, v22, 1.0
	v_rcp_f32_e32 v24, v23
	v_div_scale_f32 v25, vcc, 1.0, v22, 1.0
	v_fma_f32 v44, -v23, v24, 1.0
	v_fmac_f32_e32 v24, v44, v24
	v_mul_f32_e32 v44, v25, v24
	v_fma_f32 v45, -v23, v44, v25
	v_fmac_f32_e32 v44, v45, v24
	v_fma_f32 v23, -v23, v44, v25
	v_div_fmas_f32 v23, v23, v24, v44
	v_div_fixup_f32 v22, v23, v22, 1.0
	v_mul_f32_e32 v46, v46, v22
	ds_write_b32 v17, v46 offset:0
	s_waitcnt vmcnt(8)
	v_mul_f32_e32 v22, 0xbfb8aa3b, v47
	v_exp_f32_e32 v22, v22
	s_nop 0
	v_add_f32_e32 v22, 1.0, v22
	v_div_scale_f32 v23, s[56:57], v22, v22, 1.0
	v_rcp_f32_e32 v24, v23
	v_div_scale_f32 v25, vcc, 1.0, v22, 1.0
	v_fma_f32 v44, -v23, v24, 1.0
	v_fmac_f32_e32 v24, v44, v24
	v_mul_f32_e32 v44, v25, v24
	v_fma_f32 v45, -v23, v44, v25
	v_fmac_f32_e32 v44, v45, v24
	v_fma_f32 v23, -v23, v44, v25
	v_div_fmas_f32 v23, v23, v24, v44
	v_div_fixup_f32 v22, v23, v22, 1.0
	v_mul_f32_e32 v47, v47, v22
	ds_write_b32 v17, v47 offset:2048
	s_waitcnt vmcnt(7)
	v_mul_f32_e32 v22, 0xbfb8aa3b, v48
	v_exp_f32_e32 v22, v22
	s_nop 0
	v_add_f32_e32 v22, 1.0, v22
	v_div_scale_f32 v23, s[56:57], v22, v22, 1.0
	v_rcp_f32_e32 v24, v23
	v_div_scale_f32 v25, vcc, 1.0, v22, 1.0
	v_fma_f32 v44, -v23, v24, 1.0
	v_fmac_f32_e32 v24, v44, v24
	v_mul_f32_e32 v44, v25, v24
	v_fma_f32 v45, -v23, v44, v25
	v_fmac_f32_e32 v44, v45, v24
	v_fma_f32 v23, -v23, v44, v25
	v_div_fmas_f32 v23, v23, v24, v44
	v_div_fixup_f32 v22, v23, v22, 1.0
	v_mul_f32_e32 v48, v48, v22
	ds_write_b32 v17, v48 offset:4096
	s_waitcnt vmcnt(6)
	v_mul_f32_e32 v22, 0xbfb8aa3b, v49
	v_exp_f32_e32 v22, v22
	s_nop 0
	v_add_f32_e32 v22, 1.0, v22
	v_div_scale_f32 v23, s[56:57], v22, v22, 1.0
	v_rcp_f32_e32 v24, v23
	v_div_scale_f32 v25, vcc, 1.0, v22, 1.0
	v_fma_f32 v44, -v23, v24, 1.0
	v_fmac_f32_e32 v24, v44, v24
	v_mul_f32_e32 v44, v25, v24
	v_fma_f32 v45, -v23, v44, v25
	v_fmac_f32_e32 v44, v45, v24
	v_fma_f32 v23, -v23, v44, v25
	v_div_fmas_f32 v23, v23, v24, v44
	v_div_fixup_f32 v22, v23, v22, 1.0
	v_mul_f32_e32 v49, v49, v22
	ds_write_b32 v17, v49 offset:6144
	s_waitcnt vmcnt(5)
	v_mul_f32_e32 v22, 0xbfb8aa3b, v50
	v_exp_f32_e32 v22, v22
	s_nop 0
	v_add_f32_e32 v22, 1.0, v22
	v_div_scale_f32 v23, s[56:57], v22, v22, 1.0
	v_rcp_f32_e32 v24, v23
	v_div_scale_f32 v25, vcc, 1.0, v22, 1.0
	v_fma_f32 v44, -v23, v24, 1.0
	v_fmac_f32_e32 v24, v44, v24
	v_mul_f32_e32 v44, v25, v24
	v_fma_f32 v45, -v23, v44, v25
	v_fmac_f32_e32 v44, v45, v24
	v_fma_f32 v23, -v23, v44, v25
	v_div_fmas_f32 v23, v23, v24, v44
	v_div_fixup_f32 v22, v23, v22, 1.0
	v_mul_f32_e32 v50, v50, v22
	ds_write_b32 v17, v50 offset:8192
	s_waitcnt vmcnt(4)
	v_mul_f32_e32 v22, 0xbfb8aa3b, v51
	v_exp_f32_e32 v22, v22
	s_nop 0
	v_add_f32_e32 v22, 1.0, v22
	v_div_scale_f32 v23, s[56:57], v22, v22, 1.0
	v_rcp_f32_e32 v24, v23
	v_div_scale_f32 v25, vcc, 1.0, v22, 1.0
	v_fma_f32 v44, -v23, v24, 1.0
	v_fmac_f32_e32 v24, v44, v24
	v_mul_f32_e32 v44, v25, v24
	v_fma_f32 v45, -v23, v44, v25
	v_fmac_f32_e32 v44, v45, v24
	v_fma_f32 v23, -v23, v44, v25
	v_div_fmas_f32 v23, v23, v24, v44
	v_div_fixup_f32 v22, v23, v22, 1.0
	v_mul_f32_e32 v51, v51, v22
	ds_write_b32 v17, v51 offset:10240
	s_waitcnt vmcnt(3)
	v_mul_f32_e32 v22, 0xbfb8aa3b, v52
	v_exp_f32_e32 v22, v22
	s_nop 0
	v_add_f32_e32 v22, 1.0, v22
	v_div_scale_f32 v23, s[56:57], v22, v22, 1.0
	v_rcp_f32_e32 v24, v23
	v_div_scale_f32 v25, vcc, 1.0, v22, 1.0
	v_fma_f32 v44, -v23, v24, 1.0
	v_fmac_f32_e32 v24, v44, v24
	v_mul_f32_e32 v44, v25, v24
	v_fma_f32 v45, -v23, v44, v25
	v_fmac_f32_e32 v44, v45, v24
	v_fma_f32 v23, -v23, v44, v25
	v_div_fmas_f32 v23, v23, v24, v44
	v_div_fixup_f32 v22, v23, v22, 1.0
	v_mul_f32_e32 v52, v52, v22
	ds_write_b32 v17, v52 offset:12288
	s_waitcnt vmcnt(2)
	v_mul_f32_e32 v22, 0xbfb8aa3b, v53
	v_exp_f32_e32 v22, v22
	s_nop 0
	v_add_f32_e32 v22, 1.0, v22
	v_div_scale_f32 v23, s[56:57], v22, v22, 1.0
	v_rcp_f32_e32 v24, v23
	v_div_scale_f32 v25, vcc, 1.0, v22, 1.0
	v_fma_f32 v44, -v23, v24, 1.0
	v_fmac_f32_e32 v24, v44, v24
	v_mul_f32_e32 v44, v25, v24
	v_fma_f32 v45, -v23, v44, v25
	v_fmac_f32_e32 v44, v45, v24
	v_fma_f32 v23, -v23, v44, v25
	v_div_fmas_f32 v23, v23, v24, v44
	v_div_fixup_f32 v22, v23, v22, 1.0
	v_mul_f32_e32 v53, v53, v22
	ds_write_b32 v17, v53 offset:14336
	s_waitcnt vmcnt(1)
	v_mul_f32_e32 v22, 0xbfb8aa3b, v54
	v_exp_f32_e32 v22, v22
	s_nop 0
	v_add_f32_e32 v22, 1.0, v22
	v_div_scale_f32 v23, s[56:57], v22, v22, 1.0
	v_rcp_f32_e32 v24, v23
	v_div_scale_f32 v25, vcc, 1.0, v22, 1.0
	v_fma_f32 v44, -v23, v24, 1.0
	v_fmac_f32_e32 v24, v44, v24
	v_mul_f32_e32 v44, v25, v24
	v_fma_f32 v45, -v23, v44, v25
	v_fmac_f32_e32 v44, v45, v24
	v_fma_f32 v23, -v23, v44, v25
	v_div_fmas_f32 v23, v23, v24, v44
	v_div_fixup_f32 v22, v23, v22, 1.0
	v_mul_f32_e32 v54, v54, v22
	ds_write_b32 v17, v54 offset:16384
	s_waitcnt vmcnt(0)
	v_mul_f32_e32 v22, 0xbfb8aa3b, v55
	v_exp_f32_e32 v22, v22
	s_nop 0
	v_add_f32_e32 v22, 1.0, v22
	v_div_scale_f32 v23, s[56:57], v22, v22, 1.0
	v_rcp_f32_e32 v24, v23
	v_div_scale_f32 v25, vcc, 1.0, v22, 1.0
	v_fma_f32 v44, -v23, v24, 1.0
	v_fmac_f32_e32 v24, v44, v24
	v_mul_f32_e32 v44, v25, v24
	v_fma_f32 v45, -v23, v44, v25
	v_fmac_f32_e32 v44, v45, v24
	v_fma_f32 v23, -v23, v44, v25
	v_div_fmas_f32 v23, v23, v24, v44
	v_div_fixup_f32 v22, v23, v22, 1.0
	v_mul_f32_e32 v55, v55, v22
	ds_write_b32 v17, v55 offset:18432
	s_or_b64 exec, exec, s[0:1]
	s_mul_hi_i32 s0, s2, 0x2aaaaaab
	s_lshr_b32 s1, s0, 31
	s_ashr_i32 s52, s0, 4
	s_add_i32 s52, s52, s1
	s_mul_i32 s56, s52, 0x1800
	s_sub_i32 s0, s76, s56
	s_ashr_i32 s1, s0, 31
	s_mul_i32 s58, s52, 0x1800000
	s_lshl_b64 s[0:1], s[0:1], 2
	s_mul_hi_i32 s57, s52, 0x1800000
	s_add_u32 s0, s58, s0
	s_addc_u32 s1, s57, s1
	v_mov_b32_e32 v4, 0
	v_lshl_add_u64 v[20:21], v[12:13], 0, s[0:1]
	s_mov_b64 s[0:1], 0
	v_mov_b32_e32 v17, v38
	v_mov_b32_e32 v22, 0
	v_mov_b32_e32 v23, v4
	v_mov_b32_e32 v24, 0
	v_mov_b32_e32 v25, v4
	s_waitcnt lgkmcnt(0)
	s_barrier

.Lpk_loop:
	v_cmp_gt_u32_e32 vcc, s56, v86
	s_and_b64 exec, exec, vcc
	s_cbranch_execz .Lpk_done
	v_add_u32_e32 v87, 0x0, v86
	v_cmp_gt_u32_e32 vcc, s56, v87
	s_and_saveexec_b64 s[58:59], vcc
	global_load_dwordx4 v[88:91], v[80:81], off offset:0
	s_mov_b64 exec, s[58:59]
	v_add_u32_e32 v87, 0x1, v86
	v_cmp_gt_u32_e32 vcc, s56, v87
	s_and_saveexec_b64 s[58:59], vcc
	global_load_dwordx4 v[92:95], v[80:81], off offset:16
	s_mov_b64 exec, s[58:59]
	v_add_u32_e32 v87, 0x2, v86
	v_cmp_gt_u32_e32 vcc, s56, v87
	s_and_saveexec_b64 s[58:59], vcc
	global_load_dwordx4 v[96:99], v[80:81], off offset:32
	s_mov_b64 exec, s[58:59]
	v_add_u32_e32 v87, 0x3, v86
	v_cmp_gt_u32_e32 vcc, s56, v87
	s_and_saveexec_b64 s[58:59], vcc
	global_load_dwordx4 v[100:103], v[80:81], off offset:48
	s_mov_b64 exec, s[58:59]
	v_lshl_add_u64 v[152:153], v[80:81], 0, s[62:63]
	v_add_u32_e32 v87, 0x800, v86
	v_cmp_gt_u32_e32 vcc, s56, v87
	s_and_saveexec_b64 s[58:59], vcc
	global_load_dwordx4 v[104:107], v[152:153], off offset:0
	s_mov_b64 exec, s[58:59]
	v_add_u32_e32 v87, 0x801, v86
	v_cmp_gt_u32_e32 vcc, s56, v87
	s_and_saveexec_b64 s[58:59], vcc
	global_load_dwordx4 v[108:111], v[152:153], off offset:16
	s_mov_b64 exec, s[58:59]
	v_add_u32_e32 v87, 0x802, v86
	v_cmp_gt_u32_e32 vcc, s56, v87
	s_and_saveexec_b64 s[58:59], vcc
	global_load_dwordx4 v[112:115], v[152:153], off offset:32
	s_mov_b64 exec, s[58:59]
	v_add_u32_e32 v87, 0x803, v86
	v_cmp_gt_u32_e32 vcc, s56, v87
	s_and_saveexec_b64 s[58:59], vcc
	global_load_dwordx4 v[116:119], v[152:153], off offset:48
	s_mov_b64 exec, s[58:59]
	v_lshl_add_u64 v[154:155], v[152:153], 0, s[62:63]
	v_add_u32_e32 v87, 0x1000, v86
	v_cmp_gt_u32_e32 vcc, s56, v87
	s_and_saveexec_b64 s[58:59], vcc
	global_load_dwordx4 v[120:123], v[154:155], off offset:0
	s_mov_b64 exec, s[58:59]
	v_add_u32_e32 v87, 0x1001, v86
	v_cmp_gt_u32_e32 vcc, s56, v87
	s_and_saveexec_b64 s[58:59], vcc
	global_load_dwordx4 v[124:127], v[154:155], off offset:16
	s_mov_b64 exec, s[58:59]
	v_add_u32_e32 v87, 0x1002, v86
	v_cmp_gt_u32_e32 vcc, s56, v87
	s_and_saveexec_b64 s[58:59], vcc
	global_load_dwordx4 v[128:131], v[154:155], off offset:32
	s_mov_b64 exec, s[58:59]
	v_add_u32_e32 v87, 0x1003, v86
	v_cmp_gt_u32_e32 vcc, s56, v87
	s_and_saveexec_b64 s[58:59], vcc
	global_load_dwordx4 v[132:135], v[154:155], off offset:48
	s_mov_b64 exec, s[58:59]
	v_lshl_add_u64 v[156:157], v[154:155], 0, s[62:63]
	v_add_u32_e32 v87, 0x1800, v86
	v_cmp_gt_u32_e32 vcc, s56, v87
	s_and_saveexec_b64 s[58:59], vcc
	global_load_dwordx4 v[136:139], v[156:157], off offset:0
	s_mov_b64 exec, s[58:59]
	v_add_u32_e32 v87, 0x1801, v86
	v_cmp_gt_u32_e32 vcc, s56, v87
	s_and_saveexec_b64 s[58:59], vcc
	global_load_dwordx4 v[140:143], v[156:157], off offset:16
	s_mov_b64 exec, s[58:59]
	v_add_u32_e32 v87, 0x1802, v86
	v_cmp_gt_u32_e32 vcc, s56, v87
	s_and_saveexec_b64 s[58:59], vcc
	global_load_dwordx4 v[144:147], v[156:157], off offset:32
	s_mov_b64 exec, s[58:59]
	v_add_u32_e32 v87, 0x1803, v86
	v_cmp_gt_u32_e32 vcc, s56, v87
	s_and_saveexec_b64 s[58:59], vcc
	global_load_dwordx4 v[148:151], v[156:157], off offset:48
	s_mov_b64 exec, s[58:59]
	s_waitcnt vmcnt(0)
	v_add_u32_e32 v87, 0x0, v86
	v_cmp_gt_u32_e32 vcc, s56, v87
	s_and_saveexec_b64 s[58:59], vcc
	global_store_dwordx4 v[82:83], v[88:91], off offset:0
	s_mov_b64 exec, s[58:59]
	v_add_u32_e32 v87, 0x1, v86
	v_cmp_gt_u32_e32 vcc, s56, v87
	s_and_saveexec_b64 s[58:59], vcc
	global_store_dwordx4 v[82:83], v[92:95], off offset:16
	s_mov_b64 exec, s[58:59]
	v_add_u32_e32 v87, 0x2, v86
	v_cmp_gt_u32_e32 vcc, s56, v87
	s_and_saveexec_b64 s[58:59], vcc
	global_store_dwordx4 v[82:83], v[96:99], off offset:32
	s_mov_b64 exec, s[58:59]
	v_add_u32_e32 v87, 0x3, v86
	v_cmp_gt_u32_e32 vcc, s56, v87
	s_and_saveexec_b64 s[58:59], vcc
	global_store_dwordx4 v[82:83], v[100:103], off offset:48
	s_mov_b64 exec, s[58:59]
	v_lshl_add_u64 v[160:161], v[82:83], 0, s[62:63]
	v_add_u32_e32 v87, 0x800, v86
	v_cmp_gt_u32_e32 vcc, s56, v87
	s_and_saveexec_b64 s[58:59], vcc
	global_store_dwordx4 v[160:161], v[104:107], off offset:0
	s_mov_b64 exec, s[58:59]
	v_add_u32_e32 v87, 0x801, v86
	v_cmp_gt_u32_e32 vcc, s56, v87
	s_and_saveexec_b64 s[58:59], vcc
	global_store_dwordx4 v[160:161], v[108:111], off offset:16
	s_mov_b64 exec, s[58:59]
	v_add_u32_e32 v87, 0x802, v86
	v_cmp_gt_u32_e32 vcc, s56, v87
	s_and_saveexec_b64 s[58:59], vcc
	global_store_dwordx4 v[160:161], v[112:115], off offset:32
	s_mov_b64 exec, s[58:59]
	v_add_u32_e32 v87, 0x803, v86
	v_cmp_gt_u32_e32 vcc, s56, v87
	s_and_saveexec_b64 s[58:59], vcc
	global_store_dwordx4 v[160:161], v[116:119], off offset:48
	s_mov_b64 exec, s[58:59]
	v_lshl_add_u64 v[162:163], v[160:161], 0, s[62:63]
	v_add_u32_e32 v87, 0x1000, v86
	v_cmp_gt_u32_e32 vcc, s56, v87
	s_and_saveexec_b64 s[58:59], vcc
	global_store_dwordx4 v[162:163], v[120:123], off offset:0
	s_mov_b64 exec, s[58:59]
	v_add_u32_e32 v87, 0x1001, v86
	v_cmp_gt_u32_e32 vcc, s56, v87
	s_and_saveexec_b64 s[58:59], vcc
	global_store_dwordx4 v[162:163], v[124:127], off offset:16
	s_mov_b64 exec, s[58:59]
	v_add_u32_e32 v87, 0x1002, v86
	v_cmp_gt_u32_e32 vcc, s56, v87
	s_and_saveexec_b64 s[58:59], vcc
	global_store_dwordx4 v[162:163], v[128:131], off offset:32
	s_mov_b64 exec, s[58:59]
	v_add_u32_e32 v87, 0x1003, v86
	v_cmp_gt_u32_e32 vcc, s56, v87
	s_and_saveexec_b64 s[58:59], vcc
	global_store_dwordx4 v[162:163], v[132:135], off offset:48
	s_mov_b64 exec, s[58:59]
	v_lshl_add_u64 v[164:165], v[162:163], 0, s[62:63]
	v_add_u32_e32 v87, 0x1800, v86
	v_cmp_gt_u32_e32 vcc, s56, v87
	s_and_saveexec_b64 s[58:59], vcc
	global_store_dwordx4 v[164:165], v[136:139], off offset:0
	s_mov_b64 exec, s[58:59]
	v_add_u32_e32 v87, 0x1801, v86
	v_cmp_gt_u32_e32 vcc, s56, v87
	s_and_saveexec_b64 s[58:59], vcc
	global_store_dwordx4 v[164:165], v[140:143], off offset:16
	s_mov_b64 exec, s[58:59]
	v_add_u32_e32 v87, 0x1802, v86
	v_cmp_gt_u32_e32 vcc, s56, v87
	s_and_saveexec_b64 s[58:59], vcc
	global_store_dwordx4 v[164:165], v[144:147], off offset:32
	s_mov_b64 exec, s[58:59]
	v_add_u32_e32 v87, 0x1803, v86
	v_cmp_gt_u32_e32 vcc, s56, v87
	s_and_saveexec_b64 s[58:59], vcc
	global_store_dwordx4 v[164:165], v[148:151], off offset:48
	s_mov_b64 exec, s[58:59]
	v_add_u32_e32 v86, 0x2000, v86
	s_mov_b64 s[58:59], 0x20000
	v_lshl_add_u64 v[80:81], v[80:81], 0, s[58:59]
	v_lshl_add_u64 v[82:83], v[82:83], 0, s[58:59]
	s_branch .Lpk_loop
